# v12: v8 + hand-written G_OUT epilogue (EpiF0 int8) with 3 row-steps of residual x loads in flight
# speedup vs baseline: 1.0001x; 1.0001x over previous
;     __device__ __forceinline__ void operator()(const typename AccT<I8>::type (&acc)[2][2][4][2], const Unit& u, int wr, int wc, int fr, int fq) const {
;         const int row0 = u.pm * BM + wr * 64 + fr, col0 = u.pn * BM + wc * 32 + 4 * fq;
;         f32x4 sv[2][2];
;         if (I8) {
; #pragma unroll
;             for (int bj = 0; bj < 2; ++bj)
; #pragma unroll
;                 for (int n = 0; n < 2; ++n) sv[bj][n] = *(const f32x4*)(swc + col0 + bj * HALF + n * 16);
;         }
;         float rsv[8];
; #pragma unroll
;         for (int s = 0; s < 8; ++s) { const int r = row0 + (s >> 2) * HALF + (s & 3) * 16; float rs = 1.f; if (MODE == 1) rs = __builtin_amdgcn_rsqf(rstd[r] * (1.0f / 4096.0f) + 1e-6f); if (I8) rs *= sxr[r]; rsv[s] = rs; }
;         RowIn cur, nxt;
;         load_row(cur, (size_t)row0 * 4096 + col0);
; #pragma unroll
;         for (int s = 0; s < 8; ++s) { const int ai = s >> 2, m = s & 3; const int r = row0 + ai * HALF + m * 16; const size_t off = (size_t)r * 4096 + col0;
;                 if (s + 1 < 8) load_row(nxt, (size_t)(row0 + ((s + 1) >> 2) * HALF + ((s + 1) & 3) * 16) * 4096 + col0);
.LBB0_1724:
	s_lshl_b32 s98, s6, 4
	s_add_i32 s98, s98, s2
	s_sub_i32 s99, s98, 888
	s_cmp_lt_u32 s98, 888
	s_cselect_b32 s98, s98, s99
	s_mov_b32 s99, 0x4200000
	s_cselect_b32 s99, 0x3f600000, s99
	s_lshl_b32 s98, s98, 18
	s_add_u32 s98, s98, s99
	s_add_u32 s98, s96, s98
	s_addc_u32 s99, s97, 0
	v_and_b32_e32 v34, 63, v0
	v_lshrrev_b32_e32 v35, 6, v0
	v_lshlrev_b32_e32 v36, 4, v34
	v_lshl_add_u32 v36, v35, 15, v36
	v_lshrrev_b32_e32 v35, 8, v0
	v_and_b32_e32 v37, 15, v0
	v_lshl_add_u32 v35, v35, 6, v37
	v_lshl_add_u32 v38, s6, 8, v35
	v_bfe_u32 v35, v0, 6, 2
	v_bfe_u32 v39, v0, 4, 2
	v_lshlrev_b32_e32 v35, 5, v35
	v_lshl_add_u32 v35, v39, 2, v35
	v_lshl_add_u32 v35, s2, 8, v35
	v_lshlrev_b32_e32 v40, 13, v38
	v_lshl_add_u32 v40, v35, 1, v40
	v_lshlrev_b32_e32 v41, 2, v38
	v_xor_b32_e32 v42, 16, v34
	v_xor_b32_e32 v43, 32, v34
	v_lshlrev_b32_e32 v42, 2, v42
	v_lshlrev_b32_e32 v43, 2, v43
	v_lshlrev_b32_e32 v35, 2, v35
	global_load_dwordx4 v[162:165], v35, s[14:15] offset:0
	global_load_dwordx4 v[166:169], v35, s[14:15] offset:64
	global_load_dwordx4 v[170:173], v35, s[14:15] offset:512
	global_load_dwordx4 v[218:221], v35, s[14:15] offset:576
	global_load_dword v222, v41, s[16:17] offset:0
	global_load_dword v223, v41, s[16:17] offset:64
	global_load_dword v224, v41, s[16:17] offset:128
	global_load_dword v225, v41, s[16:17] offset:192
	global_load_dword v226, v41, s[16:17] offset:512
	global_load_dword v227, v41, s[16:17] offset:576
	global_load_dword v228, v41, s[16:17] offset:640
	global_load_dword v229, v41, s[16:17] offset:704
	v_lshl_add_u32 v44, v38, 14, v35
	v_cmp_eq_u32_e64 s[6:7], 0, v39
	v_readlane_b32 s68, v254, 40
	v_readlane_b32 s69, v254, 41
	global_load_dwordx4 v[146:149], v44, s[64:65] offset:0
	global_load_dwordx4 v[150:153], v44, s[64:65] offset:64
	global_load_dwordx4 v[154:157], v44, s[64:65] offset:512
	global_load_dwordx4 v[158:161], v44, s[64:65] offset:576
	v_add_u32_e32 v45, 0x40000, v44
	global_load_dwordx4 v[186:189], v45, s[64:65] offset:0
	global_load_dwordx4 v[190:193], v45, s[64:65] offset:64
	global_load_dwordx4 v[194:197], v45, s[64:65] offset:512
	global_load_dwordx4 v[198:201], v45, s[64:65] offset:576
	v_add_u32_e32 v45, 0x80000, v44
	global_load_dwordx4 v[202:205], v45, s[64:65] offset:0
	global_load_dwordx4 v[206:209], v45, s[64:65] offset:64
	global_load_dwordx4 v[210:213], v45, s[64:65] offset:512
	global_load_dwordx4 v[214:217], v45, s[64:65] offset:576
	v_cvt_f32_i32_e32 v142, v142
	v_cvt_f32_i32_e32 v143, v143
	v_cvt_f32_i32_e32 v144, v144
	v_cvt_f32_i32_e32 v145, v145
	v_cvt_f32_i32_e32 v138, v138
	v_cvt_f32_i32_e32 v139, v139
	v_cvt_f32_i32_e32 v140, v140
	v_cvt_f32_i32_e32 v141, v141
	v_cvt_f32_i32_e32 v134, v134
	v_cvt_f32_i32_e32 v135, v135
	v_cvt_f32_i32_e32 v136, v136
	v_cvt_f32_i32_e32 v137, v137
	v_cvt_f32_i32_e32 v130, v130
	v_cvt_f32_i32_e32 v131, v131
	v_cvt_f32_i32_e32 v132, v132
	v_cvt_f32_i32_e32 v133, v133
	v_cvt_f32_i32_e32 v126, v126
	v_cvt_f32_i32_e32 v127, v127
	v_cvt_f32_i32_e32 v128, v128
	v_cvt_f32_i32_e32 v129, v129
	v_cvt_f32_i32_e32 v122, v122
	v_cvt_f32_i32_e32 v123, v123
	v_cvt_f32_i32_e32 v124, v124
	v_cvt_f32_i32_e32 v125, v125
	v_cvt_f32_i32_e32 v118, v118
	v_cvt_f32_i32_e32 v119, v119
	v_cvt_f32_i32_e32 v120, v120
	v_cvt_f32_i32_e32 v121, v121
	v_cvt_f32_i32_e32 v114, v114
	v_cvt_f32_i32_e32 v115, v115
	v_cvt_f32_i32_e32 v116, v116
	v_cvt_f32_i32_e32 v117, v117
	v_cvt_f32_i32_e32 v110, v110
	v_cvt_f32_i32_e32 v111, v111
	v_cvt_f32_i32_e32 v112, v112
	v_cvt_f32_i32_e32 v113, v113
	v_cvt_f32_i32_e32 v106, v106
	v_cvt_f32_i32_e32 v107, v107
	v_cvt_f32_i32_e32 v108, v108
	v_cvt_f32_i32_e32 v109, v109
	v_cvt_f32_i32_e32 v102, v102
	v_cvt_f32_i32_e32 v103, v103
	v_cvt_f32_i32_e32 v104, v104
	v_cvt_f32_i32_e32 v105, v105
	v_cvt_f32_i32_e32 v98, v98
	v_cvt_f32_i32_e32 v99, v99
	v_cvt_f32_i32_e32 v100, v100
	v_cvt_f32_i32_e32 v101, v101
	v_cvt_f32_i32_e32 v94, v94
	v_cvt_f32_i32_e32 v95, v95
	v_cvt_f32_i32_e32 v96, v96
	v_cvt_f32_i32_e32 v97, v97
	v_cvt_f32_i32_e32 v90, v90
	v_cvt_f32_i32_e32 v91, v91
	v_cvt_f32_i32_e32 v92, v92
	v_cvt_f32_i32_e32 v93, v93
	v_cvt_f32_i32_e32 v86, v86
	v_cvt_f32_i32_e32 v87, v87
	v_cvt_f32_i32_e32 v88, v88
	v_cvt_f32_i32_e32 v89, v89
	v_cvt_f32_i32_e32 v82, v82
	v_cvt_f32_i32_e32 v83, v83
	v_cvt_f32_i32_e32 v84, v84
	v_cvt_f32_i32_e32 v85, v85
	v_cvt_f32_i32_e32 v78, v78
	v_cvt_f32_i32_e32 v79, v79
	v_cvt_f32_i32_e32 v80, v80
	v_cvt_f32_i32_e32 v81, v81
	v_cvt_f32_i32_e32 v74, v74
	v_cvt_f32_i32_e32 v75, v75
	v_cvt_f32_i32_e32 v76, v76
	v_cvt_f32_i32_e32 v77, v77
	v_cvt_f32_i32_e32 v70, v70
	v_cvt_f32_i32_e32 v71, v71
	v_cvt_f32_i32_e32 v72, v72
	v_cvt_f32_i32_e32 v73, v73
	v_cvt_f32_i32_e32 v66, v66
	v_cvt_f32_i32_e32 v67, v67
	v_cvt_f32_i32_e32 v68, v68
	v_cvt_f32_i32_e32 v69, v69
	v_cvt_f32_i32_e32 v58, v58
	v_cvt_f32_i32_e32 v59, v59
	v_cvt_f32_i32_e32 v60, v60
	v_cvt_f32_i32_e32 v61, v61
	v_cvt_f32_i32_e32 v54, v54
	v_cvt_f32_i32_e32 v55, v55
	v_cvt_f32_i32_e32 v56, v56
	v_cvt_f32_i32_e32 v57, v57
	v_cvt_f32_i32_e32 v50, v50
	v_cvt_f32_i32_e32 v51, v51
	v_cvt_f32_i32_e32 v52, v52
	v_cvt_f32_i32_e32 v53, v53
	v_cvt_f32_i32_e32 v46, v46
	v_cvt_f32_i32_e32 v47, v47
	v_cvt_f32_i32_e32 v48, v48
	v_cvt_f32_i32_e32 v49, v49
	v_cvt_f32_i32_e32 v30, v30
	v_cvt_f32_i32_e32 v31, v31
	v_cvt_f32_i32_e32 v32, v32
	v_cvt_f32_i32_e32 v33, v33
	v_cvt_f32_i32_e32 v26, v26
	v_cvt_f32_i32_e32 v27, v27
	v_cvt_f32_i32_e32 v28, v28
	v_cvt_f32_i32_e32 v29, v29
	v_cvt_f32_i32_e32 v22, v22
	v_cvt_f32_i32_e32 v23, v23
	v_cvt_f32_i32_e32 v24, v24
	v_cvt_f32_i32_e32 v25, v25
	v_cvt_f32_i32_e32 v18, v18
	v_cvt_f32_i32_e32 v19, v19
	v_cvt_f32_i32_e32 v20, v20
	v_cvt_f32_i32_e32 v21, v21
	v_cvt_f32_i32_e32 v14, v14
	v_cvt_f32_i32_e32 v15, v15
	v_cvt_f32_i32_e32 v16, v16
	v_cvt_f32_i32_e32 v17, v17
	v_cvt_f32_i32_e32 v10, v10
	v_cvt_f32_i32_e32 v11, v11
	v_cvt_f32_i32_e32 v12, v12
	v_cvt_f32_i32_e32 v13, v13
	v_cvt_f32_i32_e32 v6, v6
	v_cvt_f32_i32_e32 v7, v7
	v_cvt_f32_i32_e32 v8, v8
	v_cvt_f32_i32_e32 v9, v9
	v_cvt_f32_i32_e32 v2, v2
	v_cvt_f32_i32_e32 v3, v3
	v_cvt_f32_i32_e32 v4, v4
	v_cvt_f32_i32_e32 v5, v5
	s_waitcnt vmcnt(12)
; __device__ __forceinline__ unsigned cvt_pk_bf16(float lo, float hi) { unsigned r; asm volatile("s_nop 0\n\tv_cvt_pk_bf16_f32 %0, %1, %2" : "=v"(r) : "v"(lo), "v"(hi)); return r; }
; __device__ __forceinline__ f32x4 sig4(const f32x4 v) { return (f32x4){sigmoidf_(v[0]), sigmoidf_(v[1]), sigmoidf_(v[2]), sigmoidf_(v[3])}; }
;     __device__ __forceinline__ void operator()(const typename AccT<I8>::type (&acc)[2][2][4][2], const Unit& u, int wr, int wc, int fr, int fq) const {
;     ...
;         for (int s = 0; s < 8; ++s) { const int ai = s >> 2, m = s & 3; const int r = row0 + ai * HALF + m * 16; const size_t off = (size_t)r * 4096 + col0;
;                 if (s + 1 < 8) load_row(nxt, (size_t)(row0 + ((s + 1) >> 2) * HALF + ((s + 1) & 3) * 16) * 4096 + col0);
;                 const float rs = rsv[s];
;                 float ss = 0.f, mx = 0.f;
; #pragma unroll
;                 for (int bj = 0; bj < 2; ++bj)
; #pragma unroll
;                     for (int n = 0; n < 2; ++n) { const size_t o = off + bj * HALF + n * 16; const f32x4 b = cur.b[bj][n]; f32x4 v;
;                         if constexpr (I8) v = __builtin_convertvector(acc[ai][bj][m][n], f32x4) * rs * sv[bj][n]; else v = acc[ai][bj][m][n];
;                         if (MODE == 1) { const u32x2 pw = cur.pw[bj][n]; const f32x4 pp = (f32x4){bf_lo(pw.x), bf_hi(pw.x), bf_lo(pw.y), bf_hi(pw.y)}; v = sig4(I8 ? v : v * rs) * pp; }
;                         const f32x4 x = b + v; *(f32x4*)(out + o) = x;
;                         if (MODE == 0 && XB) { u32x2 w; w.x = cvt_pk_bf16(x[0], x[1]); w.y = cvt_pk_bf16(x[2], x[3]); *(u32x2*)(XB + o) = w; ss += (x[0] * x[0] + x[1] * x[1]) + (x[2] * x[2] + x[3] * x[3]);
;                             if (RM) mx = fmaxf(fmaxf(mx, fmaxf(fabsf(x[0]), fabsf(x[1]))), fmaxf(fabsf(x[2]), fabsf(x[3]))); } }
;                 if (MODE == 0 && XB) { ss += __shfl_xor(ss, 16); ss += __shfl_xor(ss, 32); if (fq == 0) unsafeAtomicAdd(SS + r, ss);
;                     if (RM) { mx = fmaxf(mx, __shfl_xor(mx, 16)); mx = fmaxf(mx, __shfl_xor(mx, 32)); if (fq == 0) atomicMax(RM + r, __builtin_bit_cast(unsigned, mx)); } }
;                 cur = nxt; }
	s_waitcnt vmcnt(8)
	v_pk_mul_f32 v[142:143], v[222:223], v[142:143] op_sel:[0,0] op_sel_hi:[0,1]
	v_pk_mul_f32 v[144:145], v[222:223], v[144:145] op_sel:[0,0] op_sel_hi:[0,1]
	v_pk_fma_f32 v[142:143], v[162:163], v[142:143], v[146:147]
	v_pk_fma_f32 v[144:145], v[164:165], v[144:145], v[148:149]
	v_pk_mul_f32 v[138:139], v[222:223], v[138:139] op_sel:[0,0] op_sel_hi:[0,1]
	v_pk_mul_f32 v[140:141], v[222:223], v[140:141] op_sel:[0,0] op_sel_hi:[0,1]
	v_pk_fma_f32 v[138:139], v[166:167], v[138:139], v[150:151]
	v_pk_fma_f32 v[140:141], v[168:169], v[140:141], v[152:153]
	v_pk_mul_f32 v[134:135], v[222:223], v[134:135] op_sel:[0,0] op_sel_hi:[0,1]
	v_pk_mul_f32 v[136:137], v[222:223], v[136:137] op_sel:[0,0] op_sel_hi:[0,1]
	v_pk_fma_f32 v[134:135], v[170:171], v[134:135], v[154:155]
	v_pk_fma_f32 v[136:137], v[172:173], v[136:137], v[156:157]
	v_pk_mul_f32 v[130:131], v[222:223], v[130:131] op_sel:[0,0] op_sel_hi:[0,1]
	v_pk_mul_f32 v[132:133], v[222:223], v[132:133] op_sel:[0,0] op_sel_hi:[0,1]
	v_pk_fma_f32 v[130:131], v[218:219], v[130:131], v[158:159]
	v_pk_fma_f32 v[132:133], v[220:221], v[132:133], v[160:161]
	v_add_u32_e32 v45, 0xc0000, v44
	global_load_dwordx4 v[146:149], v45, s[64:65] offset:0
	global_load_dwordx4 v[150:153], v45, s[64:65] offset:64
	global_load_dwordx4 v[154:157], v45, s[64:65] offset:512
	global_load_dwordx4 v[158:161], v45, s[64:65] offset:576
	global_store_dwordx4 v36, v[142:145], s[98:99] offset:0
	v_cvt_pk_bf16_f32 v240, v142, v143
	v_cvt_pk_bf16_f32 v241, v144, v145
	v_mul_f32_e32 v230, v143, v143
	v_mul_f32_e32 v231, v145, v145
	global_store_dwordx2 v40, v[240:241], s[68:69] offset:0
	v_fmac_f32_e32 v230, v142, v142
	v_fmac_f32_e32 v231, v144, v144
	v_add_f32_e32 v63, v230, v231
	v_max3_f32 v64, |v142|, |v143|, 0
	v_max3_f32 v64, |v144|, |v145|, v64
	global_store_dwordx4 v36, v[138:141], s[98:99] offset:1024
	v_cvt_pk_bf16_f32 v242, v138, v139
	v_cvt_pk_bf16_f32 v243, v140, v141
	v_mul_f32_e32 v230, v139, v139
	v_mul_f32_e32 v231, v141, v141
	global_store_dwordx2 v40, v[242:243], s[68:69] offset:32
	v_fmac_f32_e32 v230, v138, v138
	v_fmac_f32_e32 v231, v140, v140
	v_add_f32_e32 v230, v230, v231
	v_add_f32_e32 v63, v63, v230
	v_max3_f32 v64, |v138|, |v139|, v64
	v_max3_f32 v64, |v140|, |v141|, v64
	global_store_dwordx4 v36, v[134:137], s[98:99] offset:2048
	v_cvt_pk_bf16_f32 v244, v134, v135
	v_cvt_pk_bf16_f32 v245, v136, v137
	v_mul_f32_e32 v230, v135, v135
	v_mul_f32_e32 v231, v137, v137
	global_store_dwordx2 v40, v[244:245], s[68:69] offset:256
	v_fmac_f32_e32 v230, v134, v134
	v_fmac_f32_e32 v231, v136, v136
	v_add_f32_e32 v230, v230, v231
	v_add_f32_e32 v63, v63, v230
	v_max3_f32 v64, |v134|, |v135|, v64
	v_max3_f32 v64, |v136|, |v137|, v64
	global_store_dwordx4 v36, v[130:133], s[98:99] offset:3072
	v_cvt_pk_bf16_f32 v246, v130, v131
	v_cvt_pk_bf16_f32 v247, v132, v133
	v_mul_f32_e32 v230, v131, v131
	v_mul_f32_e32 v231, v133, v133
	global_store_dwordx2 v40, v[246:247], s[68:69] offset:288
	v_fmac_f32_e32 v230, v130, v130
	v_fmac_f32_e32 v231, v132, v132
	v_add_f32_e32 v230, v230, v231
	v_add_f32_e32 v63, v63, v230
	v_max3_f32 v64, |v130|, |v131|, v64
	v_max3_f32 v64, |v132|, |v133|, v64
	ds_bpermute_b32 v238, v42, v63
	ds_bpermute_b32 v239, v42, v64
	s_waitcnt lgkmcnt(0)
	v_add_f32_e32 v63, v63, v238
	v_max_f32_e32 v64, v64, v239
	ds_bpermute_b32 v238, v43, v63
	ds_bpermute_b32 v239, v43, v64
	s_waitcnt lgkmcnt(0)
	v_add_f32_e32 v63, v63, v238
	v_max_f32_e32 v64, v64, v239
	s_mov_b64 exec, s[6:7]
	global_atomic_add_f32 v41, v63, s[10:11] offset:0
	global_atomic_umax v41, v64, s[12:13] offset:0
	s_mov_b64 exec, -1
	s_waitcnt vmcnt(18)
	v_pk_mul_f32 v[126:127], v[222:223], v[126:127] op_sel:[1,0] op_sel_hi:[1,1]
	v_pk_mul_f32 v[128:129], v[222:223], v[128:129] op_sel:[1,0] op_sel_hi:[1,1]
	v_pk_fma_f32 v[126:127], v[162:163], v[126:127], v[186:187]
	v_pk_fma_f32 v[128:129], v[164:165], v[128:129], v[188:189]
	v_pk_mul_f32 v[122:123], v[222:223], v[122:123] op_sel:[1,0] op_sel_hi:[1,1]
	v_pk_mul_f32 v[124:125], v[222:223], v[124:125] op_sel:[1,0] op_sel_hi:[1,1]
	v_pk_fma_f32 v[122:123], v[166:167], v[122:123], v[190:191]
	v_pk_fma_f32 v[124:125], v[168:169], v[124:125], v[192:193]
	v_pk_mul_f32 v[118:119], v[222:223], v[118:119] op_sel:[1,0] op_sel_hi:[1,1]
	v_pk_mul_f32 v[120:121], v[222:223], v[120:121] op_sel:[1,0] op_sel_hi:[1,1]
	v_pk_fma_f32 v[118:119], v[170:171], v[118:119], v[194:195]
	v_pk_fma_f32 v[120:121], v[172:173], v[120:121], v[196:197]
	v_pk_mul_f32 v[114:115], v[222:223], v[114:115] op_sel:[1,0] op_sel_hi:[1,1]
	v_pk_mul_f32 v[116:117], v[222:223], v[116:117] op_sel:[1,0] op_sel_hi:[1,1]
	v_pk_fma_f32 v[114:115], v[218:219], v[114:115], v[198:199]
	v_pk_fma_f32 v[116:117], v[220:221], v[116:117], v[200:201]
	v_add_u32_e32 v45, 0x200000, v44
	global_load_dwordx4 v[186:189], v45, s[64:65] offset:0
	global_load_dwordx4 v[190:193], v45, s[64:65] offset:64
	global_load_dwordx4 v[194:197], v45, s[64:65] offset:512
	global_load_dwordx4 v[198:201], v45, s[64:65] offset:576
	v_add_u32_e32 v62, 0x1000, v36
	v_add_u32_e32 v65, 0x20000, v40
	global_store_dwordx4 v62, v[126:129], s[98:99] offset:0
	v_cvt_pk_bf16_f32 v240, v126, v127
	v_cvt_pk_bf16_f32 v241, v128, v129
	v_mul_f32_e32 v230, v127, v127
	v_mul_f32_e32 v231, v129, v129
	global_store_dwordx2 v65, v[240:241], s[68:69] offset:0
	v_fmac_f32_e32 v230, v126, v126
	v_fmac_f32_e32 v231, v128, v128
	v_add_f32_e32 v63, v230, v231
	v_max3_f32 v64, |v126|, |v127|, 0
	v_max3_f32 v64, |v128|, |v129|, v64
	global_store_dwordx4 v62, v[122:125], s[98:99] offset:1024
	v_cvt_pk_bf16_f32 v242, v122, v123
	v_cvt_pk_bf16_f32 v243, v124, v125
	v_mul_f32_e32 v230, v123, v123
	v_mul_f32_e32 v231, v125, v125
	global_store_dwordx2 v65, v[242:243], s[68:69] offset:32
	v_fmac_f32_e32 v230, v122, v122
	v_fmac_f32_e32 v231, v124, v124
	v_add_f32_e32 v230, v230, v231
	v_add_f32_e32 v63, v63, v230
	v_max3_f32 v64, |v122|, |v123|, v64
	v_max3_f32 v64, |v124|, |v125|, v64
	global_store_dwordx4 v62, v[118:121], s[98:99] offset:2048
	v_cvt_pk_bf16_f32 v244, v118, v119
	v_cvt_pk_bf16_f32 v245, v120, v121
	v_mul_f32_e32 v230, v119, v119
	v_mul_f32_e32 v231, v121, v121
	global_store_dwordx2 v65, v[244:245], s[68:69] offset:256
	v_fmac_f32_e32 v230, v118, v118
	v_fmac_f32_e32 v231, v120, v120
	v_add_f32_e32 v230, v230, v231
	v_add_f32_e32 v63, v63, v230
	v_max3_f32 v64, |v118|, |v119|, v64
	v_max3_f32 v64, |v120|, |v121|, v64
	global_store_dwordx4 v62, v[114:117], s[98:99] offset:3072
	v_cvt_pk_bf16_f32 v246, v114, v115
	v_cvt_pk_bf16_f32 v247, v116, v117
	v_mul_f32_e32 v230, v115, v115
	v_mul_f32_e32 v231, v117, v117
	global_store_dwordx2 v65, v[246:247], s[68:69] offset:288
	v_fmac_f32_e32 v230, v114, v114
	v_fmac_f32_e32 v231, v116, v116
	v_add_f32_e32 v230, v230, v231
	v_add_f32_e32 v63, v63, v230
	v_max3_f32 v64, |v114|, |v115|, v64
	v_max3_f32 v64, |v116|, |v117|, v64
	ds_bpermute_b32 v238, v42, v63
	ds_bpermute_b32 v239, v42, v64
	s_waitcnt lgkmcnt(0)
; __device__ __forceinline__ unsigned cvt_pk_bf16(float lo, float hi) { unsigned r; asm volatile("s_nop 0\n\tv_cvt_pk_bf16_f32 %0, %1, %2" : "=v"(r) : "v"(lo), "v"(hi)); return r; }
; __device__ __forceinline__ f32x4 sig4(const f32x4 v) { return (f32x4){sigmoidf_(v[0]), sigmoidf_(v[1]), sigmoidf_(v[2]), sigmoidf_(v[3])}; }
;     __device__ __forceinline__ void operator()(const typename AccT<I8>::type (&acc)[2][2][4][2], const Unit& u, int wr, int wc, int fr, int fq) const {
;     ...
;         for (int s = 0; s < 8; ++s) { const int ai = s >> 2, m = s & 3; const int r = row0 + ai * HALF + m * 16; const size_t off = (size_t)r * 4096 + col0;
;                 if (s + 1 < 8) load_row(nxt, (size_t)(row0 + ((s + 1) >> 2) * HALF + ((s + 1) & 3) * 16) * 4096 + col0);
;                 const float rs = rsv[s];
;                 float ss = 0.f, mx = 0.f;
; #pragma unroll
;                 for (int bj = 0; bj < 2; ++bj)
; #pragma unroll
;                     for (int n = 0; n < 2; ++n) { const size_t o = off + bj * HALF + n * 16; const f32x4 b = cur.b[bj][n]; f32x4 v;
;                         if constexpr (I8) v = __builtin_convertvector(acc[ai][bj][m][n], f32x4) * rs * sv[bj][n]; else v = acc[ai][bj][m][n];
;                         if (MODE == 1) { const u32x2 pw = cur.pw[bj][n]; const f32x4 pp = (f32x4){bf_lo(pw.x), bf_hi(pw.x), bf_lo(pw.y), bf_hi(pw.y)}; v = sig4(I8 ? v : v * rs) * pp; }
;                         const f32x4 x = b + v; *(f32x4*)(out + o) = x;
;                         if (MODE == 0 && XB) { u32x2 w; w.x = cvt_pk_bf16(x[0], x[1]); w.y = cvt_pk_bf16(x[2], x[3]); *(u32x2*)(XB + o) = w; ss += (x[0] * x[0] + x[1] * x[1]) + (x[2] * x[2] + x[3] * x[3]);
;                             if (RM) mx = fmaxf(fmaxf(mx, fmaxf(fabsf(x[0]), fabsf(x[1]))), fmaxf(fabsf(x[2]), fabsf(x[3]))); } }
;                 if (MODE == 0 && XB) { ss += __shfl_xor(ss, 16); ss += __shfl_xor(ss, 32); if (fq == 0) unsafeAtomicAdd(SS + r, ss);
;                     if (RM) { mx = fmaxf(mx, __shfl_xor(mx, 16)); mx = fmaxf(mx, __shfl_xor(mx, 32)); if (fq == 0) atomicMax(RM + r, __builtin_bit_cast(unsigned, mx)); } }
;                 cur = nxt; }
	v_add_f32_e32 v63, v63, v238
	v_max_f32_e32 v64, v64, v239
	ds_bpermute_b32 v238, v43, v63
	ds_bpermute_b32 v239, v43, v64
	s_waitcnt lgkmcnt(0)
	v_add_f32_e32 v63, v63, v238
	v_max_f32_e32 v64, v64, v239
	s_mov_b64 exec, s[6:7]
	global_atomic_add_f32 v41, v63, s[10:11] offset:64
	global_atomic_umax v41, v64, s[12:13] offset:64
	s_mov_b64 exec, -1
	s_waitcnt vmcnt(28)
	v_pk_mul_f32 v[110:111], v[224:225], v[110:111] op_sel:[0,0] op_sel_hi:[0,1]
	v_pk_mul_f32 v[112:113], v[224:225], v[112:113] op_sel:[0,0] op_sel_hi:[0,1]
	v_pk_fma_f32 v[110:111], v[162:163], v[110:111], v[202:203]
	v_pk_fma_f32 v[112:113], v[164:165], v[112:113], v[204:205]
	v_pk_mul_f32 v[106:107], v[224:225], v[106:107] op_sel:[0,0] op_sel_hi:[0,1]
	v_pk_mul_f32 v[108:109], v[224:225], v[108:109] op_sel:[0,0] op_sel_hi:[0,1]
	v_pk_fma_f32 v[106:107], v[166:167], v[106:107], v[206:207]
	v_pk_fma_f32 v[108:109], v[168:169], v[108:109], v[208:209]
	v_pk_mul_f32 v[102:103], v[224:225], v[102:103] op_sel:[0,0] op_sel_hi:[0,1]
	v_pk_mul_f32 v[104:105], v[224:225], v[104:105] op_sel:[0,0] op_sel_hi:[0,1]
	v_pk_fma_f32 v[102:103], v[170:171], v[102:103], v[210:211]
	v_pk_fma_f32 v[104:105], v[172:173], v[104:105], v[212:213]
	v_pk_mul_f32 v[98:99], v[224:225], v[98:99] op_sel:[0,0] op_sel_hi:[0,1]
	v_pk_mul_f32 v[100:101], v[224:225], v[100:101] op_sel:[0,0] op_sel_hi:[0,1]
	v_pk_fma_f32 v[98:99], v[218:219], v[98:99], v[214:215]
	v_pk_fma_f32 v[100:101], v[220:221], v[100:101], v[216:217]
	v_add_u32_e32 v45, 0x240000, v44
	global_load_dwordx4 v[202:205], v45, s[64:65] offset:0
	global_load_dwordx4 v[206:209], v45, s[64:65] offset:64
	global_load_dwordx4 v[210:213], v45, s[64:65] offset:512
	global_load_dwordx4 v[214:217], v45, s[64:65] offset:576
	v_add_u32_e32 v62, 0x2000, v36
	v_add_u32_e32 v65, 0x40000, v40
	global_store_dwordx4 v62, v[110:113], s[98:99] offset:0
	v_cvt_pk_bf16_f32 v240, v110, v111
	v_cvt_pk_bf16_f32 v241, v112, v113
	v_mul_f32_e32 v230, v111, v111
	v_mul_f32_e32 v231, v113, v113
	global_store_dwordx2 v65, v[240:241], s[68:69] offset:0
	v_fmac_f32_e32 v230, v110, v110
	v_fmac_f32_e32 v231, v112, v112
	v_add_f32_e32 v63, v230, v231
	v_max3_f32 v64, |v110|, |v111|, 0
	v_max3_f32 v64, |v112|, |v113|, v64
	global_store_dwordx4 v62, v[106:109], s[98:99] offset:1024
	v_cvt_pk_bf16_f32 v242, v106, v107
	v_cvt_pk_bf16_f32 v243, v108, v109
	v_mul_f32_e32 v230, v107, v107
	v_mul_f32_e32 v231, v109, v109
	global_store_dwordx2 v65, v[242:243], s[68:69] offset:32
	v_fmac_f32_e32 v230, v106, v106
	v_fmac_f32_e32 v231, v108, v108
	v_add_f32_e32 v230, v230, v231
	v_add_f32_e32 v63, v63, v230
	v_max3_f32 v64, |v106|, |v107|, v64
	v_max3_f32 v64, |v108|, |v109|, v64
	global_store_dwordx4 v62, v[102:105], s[98:99] offset:2048
	v_cvt_pk_bf16_f32 v244, v102, v103
	v_cvt_pk_bf16_f32 v245, v104, v105
	v_mul_f32_e32 v230, v103, v103
	v_mul_f32_e32 v231, v105, v105
	global_store_dwordx2 v65, v[244:245], s[68:69] offset:256
	v_fmac_f32_e32 v230, v102, v102
	v_fmac_f32_e32 v231, v104, v104
	v_add_f32_e32 v230, v230, v231
	v_add_f32_e32 v63, v63, v230
	v_max3_f32 v64, |v102|, |v103|, v64
	v_max3_f32 v64, |v104|, |v105|, v64
	global_store_dwordx4 v62, v[98:101], s[98:99] offset:3072
	v_cvt_pk_bf16_f32 v246, v98, v99
	v_cvt_pk_bf16_f32 v247, v100, v101
	v_mul_f32_e32 v230, v99, v99
	v_mul_f32_e32 v231, v101, v101
	global_store_dwordx2 v65, v[246:247], s[68:69] offset:288
	v_fmac_f32_e32 v230, v98, v98
	v_fmac_f32_e32 v231, v100, v100
	v_add_f32_e32 v230, v230, v231
	v_add_f32_e32 v63, v63, v230
	v_max3_f32 v64, |v98|, |v99|, v64
	v_max3_f32 v64, |v100|, |v101|, v64
	ds_bpermute_b32 v238, v42, v63
	ds_bpermute_b32 v239, v42, v64
	s_waitcnt lgkmcnt(0)
	v_add_f32_e32 v63, v63, v238
	v_max_f32_e32 v64, v64, v239
	ds_bpermute_b32 v238, v43, v63
	ds_bpermute_b32 v239, v43, v64
	s_waitcnt lgkmcnt(0)
	v_add_f32_e32 v63, v63, v238
	v_max_f32_e32 v64, v64, v239
	s_mov_b64 exec, s[6:7]
	global_atomic_add_f32 v41, v63, s[10:11] offset:128
	global_atomic_umax v41, v64, s[12:13] offset:128
	s_mov_b64 exec, -1
	s_waitcnt vmcnt(38)
	v_pk_mul_f32 v[94:95], v[224:225], v[94:95] op_sel:[1,0] op_sel_hi:[1,1]
	v_pk_mul_f32 v[96:97], v[224:225], v[96:97] op_sel:[1,0] op_sel_hi:[1,1]
	v_pk_fma_f32 v[94:95], v[162:163], v[94:95], v[146:147]
	v_pk_fma_f32 v[96:97], v[164:165], v[96:97], v[148:149]
	v_pk_mul_f32 v[90:91], v[224:225], v[90:91] op_sel:[1,0] op_sel_hi:[1,1]
	v_pk_mul_f32 v[92:93], v[224:225], v[92:93] op_sel:[1,0] op_sel_hi:[1,1]
	v_pk_fma_f32 v[90:91], v[166:167], v[90:91], v[150:151]
	v_pk_fma_f32 v[92:93], v[168:169], v[92:93], v[152:153]
	v_pk_mul_f32 v[86:87], v[224:225], v[86:87] op_sel:[1,0] op_sel_hi:[1,1]
	v_pk_mul_f32 v[88:89], v[224:225], v[88:89] op_sel:[1,0] op_sel_hi:[1,1]
	v_pk_fma_f32 v[86:87], v[170:171], v[86:87], v[154:155]
	v_pk_fma_f32 v[88:89], v[172:173], v[88:89], v[156:157]
	v_pk_mul_f32 v[82:83], v[224:225], v[82:83] op_sel:[1,0] op_sel_hi:[1,1]
	v_pk_mul_f32 v[84:85], v[224:225], v[84:85] op_sel:[1,0] op_sel_hi:[1,1]
	v_pk_fma_f32 v[82:83], v[218:219], v[82:83], v[158:159]
	v_pk_fma_f32 v[84:85], v[220:221], v[84:85], v[160:161]
	v_add_u32_e32 v45, 0x280000, v44
	global_load_dwordx4 v[146:149], v45, s[64:65] offset:0
	global_load_dwordx4 v[150:153], v45, s[64:65] offset:64
	global_load_dwordx4 v[154:157], v45, s[64:65] offset:512
	global_load_dwordx4 v[158:161], v45, s[64:65] offset:576
	v_add_u32_e32 v62, 0x3000, v36
	v_add_u32_e32 v65, 0x60000, v40
	global_store_dwordx4 v62, v[94:97], s[98:99] offset:0
	v_cvt_pk_bf16_f32 v240, v94, v95
	v_cvt_pk_bf16_f32 v241, v96, v97
	v_mul_f32_e32 v230, v95, v95
	v_mul_f32_e32 v231, v97, v97
	global_store_dwordx2 v65, v[240:241], s[68:69] offset:0
; __device__ __forceinline__ unsigned cvt_pk_bf16(float lo, float hi) { unsigned r; asm volatile("s_nop 0\n\tv_cvt_pk_bf16_f32 %0, %1, %2" : "=v"(r) : "v"(lo), "v"(hi)); return r; }
; __device__ __forceinline__ f32x4 sig4(const f32x4 v) { return (f32x4){sigmoidf_(v[0]), sigmoidf_(v[1]), sigmoidf_(v[2]), sigmoidf_(v[3])}; }
;     __device__ __forceinline__ void operator()(const typename AccT<I8>::type (&acc)[2][2][4][2], const Unit& u, int wr, int wc, int fr, int fq) const {
;     ...
;         for (int s = 0; s < 8; ++s) { const int ai = s >> 2, m = s & 3; const int r = row0 + ai * HALF + m * 16; const size_t off = (size_t)r * 4096 + col0;
;                 if (s + 1 < 8) load_row(nxt, (size_t)(row0 + ((s + 1) >> 2) * HALF + ((s + 1) & 3) * 16) * 4096 + col0);
;                 const float rs = rsv[s];
;                 float ss = 0.f, mx = 0.f;
; #pragma unroll
;                 for (int bj = 0; bj < 2; ++bj)
; #pragma unroll
;                     for (int n = 0; n < 2; ++n) { const size_t o = off + bj * HALF + n * 16; const f32x4 b = cur.b[bj][n]; f32x4 v;
;                         if constexpr (I8) v = __builtin_convertvector(acc[ai][bj][m][n], f32x4) * rs * sv[bj][n]; else v = acc[ai][bj][m][n];
;                         if (MODE == 1) { const u32x2 pw = cur.pw[bj][n]; const f32x4 pp = (f32x4){bf_lo(pw.x), bf_hi(pw.x), bf_lo(pw.y), bf_hi(pw.y)}; v = sig4(I8 ? v : v * rs) * pp; }
;                         const f32x4 x = b + v; *(f32x4*)(out + o) = x;
;                         if (MODE == 0 && XB) { u32x2 w; w.x = cvt_pk_bf16(x[0], x[1]); w.y = cvt_pk_bf16(x[2], x[3]); *(u32x2*)(XB + o) = w; ss += (x[0] * x[0] + x[1] * x[1]) + (x[2] * x[2] + x[3] * x[3]);
;                             if (RM) mx = fmaxf(fmaxf(mx, fmaxf(fabsf(x[0]), fabsf(x[1]))), fmaxf(fabsf(x[2]), fabsf(x[3]))); } }
;                 if (MODE == 0 && XB) { ss += __shfl_xor(ss, 16); ss += __shfl_xor(ss, 32); if (fq == 0) unsafeAtomicAdd(SS + r, ss);
;                     if (RM) { mx = fmaxf(mx, __shfl_xor(mx, 16)); mx = fmaxf(mx, __shfl_xor(mx, 32)); if (fq == 0) atomicMax(RM + r, __builtin_bit_cast(unsigned, mx)); } }
;                 cur = nxt; }
	v_fmac_f32_e32 v230, v94, v94
	v_fmac_f32_e32 v231, v96, v96
	v_add_f32_e32 v63, v230, v231
	v_max3_f32 v64, |v94|, |v95|, 0
	v_max3_f32 v64, |v96|, |v97|, v64
	global_store_dwordx4 v62, v[90:93], s[98:99] offset:1024
	v_cvt_pk_bf16_f32 v242, v90, v91
	v_cvt_pk_bf16_f32 v243, v92, v93
	v_mul_f32_e32 v230, v91, v91
	v_mul_f32_e32 v231, v93, v93
	global_store_dwordx2 v65, v[242:243], s[68:69] offset:32
	v_fmac_f32_e32 v230, v90, v90
	v_fmac_f32_e32 v231, v92, v92
	v_add_f32_e32 v230, v230, v231
	v_add_f32_e32 v63, v63, v230
	v_max3_f32 v64, |v90|, |v91|, v64
	v_max3_f32 v64, |v92|, |v93|, v64
	global_store_dwordx4 v62, v[86:89], s[98:99] offset:2048
	v_cvt_pk_bf16_f32 v244, v86, v87
	v_cvt_pk_bf16_f32 v245, v88, v89
	v_mul_f32_e32 v230, v87, v87
	v_mul_f32_e32 v231, v89, v89
	global_store_dwordx2 v65, v[244:245], s[68:69] offset:256
	v_fmac_f32_e32 v230, v86, v86
	v_fmac_f32_e32 v231, v88, v88
	v_add_f32_e32 v230, v230, v231
	v_add_f32_e32 v63, v63, v230
	v_max3_f32 v64, |v86|, |v87|, v64
	v_max3_f32 v64, |v88|, |v89|, v64
	global_store_dwordx4 v62, v[82:85], s[98:99] offset:3072
	v_cvt_pk_bf16_f32 v246, v82, v83
	v_cvt_pk_bf16_f32 v247, v84, v85
	v_mul_f32_e32 v230, v83, v83
	v_mul_f32_e32 v231, v85, v85
	global_store_dwordx2 v65, v[246:247], s[68:69] offset:288
	v_fmac_f32_e32 v230, v82, v82
	v_fmac_f32_e32 v231, v84, v84
	v_add_f32_e32 v230, v230, v231
	v_add_f32_e32 v63, v63, v230
	v_max3_f32 v64, |v82|, |v83|, v64
	v_max3_f32 v64, |v84|, |v85|, v64
	ds_bpermute_b32 v238, v42, v63
	ds_bpermute_b32 v239, v42, v64
	s_waitcnt lgkmcnt(0)
	v_add_f32_e32 v63, v63, v238
	v_max_f32_e32 v64, v64, v239
	ds_bpermute_b32 v238, v43, v63
	ds_bpermute_b32 v239, v43, v64
	s_waitcnt lgkmcnt(0)
	v_add_f32_e32 v63, v63, v238
	v_max_f32_e32 v64, v64, v239
	s_mov_b64 exec, s[6:7]
	global_atomic_add_f32 v41, v63, s[10:11] offset:192
	global_atomic_umax v41, v64, s[12:13] offset:192
	s_mov_b64 exec, -1
	s_waitcnt vmcnt(38)
	v_pk_mul_f32 v[78:79], v[226:227], v[78:79] op_sel:[0,0] op_sel_hi:[0,1]
	v_pk_mul_f32 v[80:81], v[226:227], v[80:81] op_sel:[0,0] op_sel_hi:[0,1]
	v_pk_fma_f32 v[78:79], v[162:163], v[78:79], v[186:187]
	v_pk_fma_f32 v[80:81], v[164:165], v[80:81], v[188:189]
	v_pk_mul_f32 v[74:75], v[226:227], v[74:75] op_sel:[0,0] op_sel_hi:[0,1]
	v_pk_mul_f32 v[76:77], v[226:227], v[76:77] op_sel:[0,0] op_sel_hi:[0,1]
	v_pk_fma_f32 v[74:75], v[166:167], v[74:75], v[190:191]
	v_pk_fma_f32 v[76:77], v[168:169], v[76:77], v[192:193]
	v_pk_mul_f32 v[70:71], v[226:227], v[70:71] op_sel:[0,0] op_sel_hi:[0,1]
	v_pk_mul_f32 v[72:73], v[226:227], v[72:73] op_sel:[0,0] op_sel_hi:[0,1]
	v_pk_fma_f32 v[70:71], v[170:171], v[70:71], v[194:195]
	v_pk_fma_f32 v[72:73], v[172:173], v[72:73], v[196:197]
	v_pk_mul_f32 v[66:67], v[226:227], v[66:67] op_sel:[0,0] op_sel_hi:[0,1]
	v_pk_mul_f32 v[68:69], v[226:227], v[68:69] op_sel:[0,0] op_sel_hi:[0,1]
	v_pk_fma_f32 v[66:67], v[218:219], v[66:67], v[198:199]
	v_pk_fma_f32 v[68:69], v[220:221], v[68:69], v[200:201]
	v_add_u32_e32 v45, 0x2c0000, v44
	global_load_dwordx4 v[186:189], v45, s[64:65] offset:0
	global_load_dwordx4 v[190:193], v45, s[64:65] offset:64
	global_load_dwordx4 v[194:197], v45, s[64:65] offset:512
	global_load_dwordx4 v[198:201], v45, s[64:65] offset:576
	v_add_u32_e32 v62, 0x4000, v36
	v_add_u32_e32 v65, 0x100000, v40
	global_store_dwordx4 v62, v[78:81], s[98:99] offset:0
	v_cvt_pk_bf16_f32 v240, v78, v79
	v_cvt_pk_bf16_f32 v241, v80, v81
	v_mul_f32_e32 v230, v79, v79
	v_mul_f32_e32 v231, v81, v81
	global_store_dwordx2 v65, v[240:241], s[68:69] offset:0
	v_fmac_f32_e32 v230, v78, v78
	v_fmac_f32_e32 v231, v80, v80
	v_add_f32_e32 v63, v230, v231
	v_max3_f32 v64, |v78|, |v79|, 0
	v_max3_f32 v64, |v80|, |v81|, v64
	global_store_dwordx4 v62, v[74:77], s[98:99] offset:1024
	v_cvt_pk_bf16_f32 v242, v74, v75
	v_cvt_pk_bf16_f32 v243, v76, v77
	v_mul_f32_e32 v230, v75, v75
	v_mul_f32_e32 v231, v77, v77
	global_store_dwordx2 v65, v[242:243], s[68:69] offset:32
	v_fmac_f32_e32 v230, v74, v74
	v_fmac_f32_e32 v231, v76, v76
	v_add_f32_e32 v230, v230, v231
	v_add_f32_e32 v63, v63, v230
	v_max3_f32 v64, |v74|, |v75|, v64
	v_max3_f32 v64, |v76|, |v77|, v64
	global_store_dwordx4 v62, v[70:73], s[98:99] offset:2048
	v_cvt_pk_bf16_f32 v244, v70, v71
	v_cvt_pk_bf16_f32 v245, v72, v73
	v_mul_f32_e32 v230, v71, v71
	v_mul_f32_e32 v231, v73, v73
	global_store_dwordx2 v65, v[244:245], s[68:69] offset:256
	v_fmac_f32_e32 v230, v70, v70
	v_fmac_f32_e32 v231, v72, v72
	v_add_f32_e32 v230, v230, v231
	v_add_f32_e32 v63, v63, v230
	v_max3_f32 v64, |v70|, |v71|, v64
	v_max3_f32 v64, |v72|, |v73|, v64
	global_store_dwordx4 v62, v[66:69], s[98:99] offset:3072
	v_cvt_pk_bf16_f32 v246, v66, v67
	v_cvt_pk_bf16_f32 v247, v68, v69
	v_mul_f32_e32 v230, v67, v67
	v_mul_f32_e32 v231, v69, v69
	global_store_dwordx2 v65, v[246:247], s[68:69] offset:288
	v_fmac_f32_e32 v230, v66, v66
	v_fmac_f32_e32 v231, v68, v68
	v_add_f32_e32 v230, v230, v231
	v_add_f32_e32 v63, v63, v230
	v_max3_f32 v64, |v66|, |v67|, v64
	v_max3_f32 v64, |v68|, |v69|, v64
	ds_bpermute_b32 v238, v42, v63
	ds_bpermute_b32 v239, v42, v64
	s_waitcnt lgkmcnt(0)
	v_add_f32_e32 v63, v63, v238
	v_max_f32_e32 v64, v64, v239
	ds_bpermute_b32 v238, v43, v63
	ds_bpermute_b32 v239, v43, v64
	s_waitcnt lgkmcnt(0)
	v_add_f32_e32 v63, v63, v238
	v_max_f32_e32 v64, v64, v239
	s_mov_b64 exec, s[6:7]
	global_atomic_add_f32 v41, v63, s[10:11] offset:512
	global_atomic_umax v41, v64, s[12:13] offset:512
	s_mov_b64 exec, -1
	s_waitcnt vmcnt(38)
; __device__ __forceinline__ unsigned cvt_pk_bf16(float lo, float hi) { unsigned r; asm volatile("s_nop 0\n\tv_cvt_pk_bf16_f32 %0, %1, %2" : "=v"(r) : "v"(lo), "v"(hi)); return r; }
; __device__ __forceinline__ f32x4 sig4(const f32x4 v) { return (f32x4){sigmoidf_(v[0]), sigmoidf_(v[1]), sigmoidf_(v[2]), sigmoidf_(v[3])}; }
;     __device__ __forceinline__ void operator()(const typename AccT<I8>::type (&acc)[2][2][4][2], const Unit& u, int wr, int wc, int fr, int fq) const {
;     ...
;         for (int s = 0; s < 8; ++s) { const int ai = s >> 2, m = s & 3; const int r = row0 + ai * HALF + m * 16; const size_t off = (size_t)r * 4096 + col0;
;                 if (s + 1 < 8) load_row(nxt, (size_t)(row0 + ((s + 1) >> 2) * HALF + ((s + 1) & 3) * 16) * 4096 + col0);
;                 const float rs = rsv[s];
;                 float ss = 0.f, mx = 0.f;
; #pragma unroll
;                 for (int bj = 0; bj < 2; ++bj)
; #pragma unroll
;                     for (int n = 0; n < 2; ++n) { const size_t o = off + bj * HALF + n * 16; const f32x4 b = cur.b[bj][n]; f32x4 v;
;                         if constexpr (I8) v = __builtin_convertvector(acc[ai][bj][m][n], f32x4) * rs * sv[bj][n]; else v = acc[ai][bj][m][n];
;                         if (MODE == 1) { const u32x2 pw = cur.pw[bj][n]; const f32x4 pp = (f32x4){bf_lo(pw.x), bf_hi(pw.x), bf_lo(pw.y), bf_hi(pw.y)}; v = sig4(I8 ? v : v * rs) * pp; }
;                         const f32x4 x = b + v; *(f32x4*)(out + o) = x;
;                         if (MODE == 0 && XB) { u32x2 w; w.x = cvt_pk_bf16(x[0], x[1]); w.y = cvt_pk_bf16(x[2], x[3]); *(u32x2*)(XB + o) = w; ss += (x[0] * x[0] + x[1] * x[1]) + (x[2] * x[2] + x[3] * x[3]);
;                             if (RM) mx = fmaxf(fmaxf(mx, fmaxf(fabsf(x[0]), fabsf(x[1]))), fmaxf(fabsf(x[2]), fabsf(x[3]))); } }
;                 if (MODE == 0 && XB) { ss += __shfl_xor(ss, 16); ss += __shfl_xor(ss, 32); if (fq == 0) unsafeAtomicAdd(SS + r, ss);
;                     if (RM) { mx = fmaxf(mx, __shfl_xor(mx, 16)); mx = fmaxf(mx, __shfl_xor(mx, 32)); if (fq == 0) atomicMax(RM + r, __builtin_bit_cast(unsigned, mx)); } }
;                 cur = nxt; }
	v_pk_mul_f32 v[58:59], v[226:227], v[58:59] op_sel:[1,0] op_sel_hi:[1,1]
	v_pk_mul_f32 v[60:61], v[226:227], v[60:61] op_sel:[1,0] op_sel_hi:[1,1]
	v_pk_fma_f32 v[58:59], v[162:163], v[58:59], v[202:203]
	v_pk_fma_f32 v[60:61], v[164:165], v[60:61], v[204:205]
	v_pk_mul_f32 v[54:55], v[226:227], v[54:55] op_sel:[1,0] op_sel_hi:[1,1]
	v_pk_mul_f32 v[56:57], v[226:227], v[56:57] op_sel:[1,0] op_sel_hi:[1,1]
	v_pk_fma_f32 v[54:55], v[166:167], v[54:55], v[206:207]
	v_pk_fma_f32 v[56:57], v[168:169], v[56:57], v[208:209]
	v_pk_mul_f32 v[50:51], v[226:227], v[50:51] op_sel:[1,0] op_sel_hi:[1,1]
	v_pk_mul_f32 v[52:53], v[226:227], v[52:53] op_sel:[1,0] op_sel_hi:[1,1]
	v_pk_fma_f32 v[50:51], v[170:171], v[50:51], v[210:211]
	v_pk_fma_f32 v[52:53], v[172:173], v[52:53], v[212:213]
	v_pk_mul_f32 v[46:47], v[226:227], v[46:47] op_sel:[1,0] op_sel_hi:[1,1]
	v_pk_mul_f32 v[48:49], v[226:227], v[48:49] op_sel:[1,0] op_sel_hi:[1,1]
	v_pk_fma_f32 v[46:47], v[218:219], v[46:47], v[214:215]
	v_pk_fma_f32 v[48:49], v[220:221], v[48:49], v[216:217]
	v_add_u32_e32 v62, 0x5000, v36
	v_add_u32_e32 v65, 0x120000, v40
	global_store_dwordx4 v62, v[58:61], s[98:99] offset:0
	v_cvt_pk_bf16_f32 v240, v58, v59
	v_cvt_pk_bf16_f32 v241, v60, v61
	v_mul_f32_e32 v230, v59, v59
	v_mul_f32_e32 v231, v61, v61
	global_store_dwordx2 v65, v[240:241], s[68:69] offset:0
	v_fmac_f32_e32 v230, v58, v58
	v_fmac_f32_e32 v231, v60, v60
	v_add_f32_e32 v63, v230, v231
	v_max3_f32 v64, |v58|, |v59|, 0
	v_max3_f32 v64, |v60|, |v61|, v64
	global_store_dwordx4 v62, v[54:57], s[98:99] offset:1024
	v_cvt_pk_bf16_f32 v242, v54, v55
	v_cvt_pk_bf16_f32 v243, v56, v57
	v_mul_f32_e32 v230, v55, v55
	v_mul_f32_e32 v231, v57, v57
	global_store_dwordx2 v65, v[242:243], s[68:69] offset:32
	v_fmac_f32_e32 v230, v54, v54
	v_fmac_f32_e32 v231, v56, v56
	v_add_f32_e32 v230, v230, v231
	v_add_f32_e32 v63, v63, v230
	v_max3_f32 v64, |v54|, |v55|, v64
	v_max3_f32 v64, |v56|, |v57|, v64
	global_store_dwordx4 v62, v[50:53], s[98:99] offset:2048
	v_cvt_pk_bf16_f32 v244, v50, v51
	v_cvt_pk_bf16_f32 v245, v52, v53
	v_mul_f32_e32 v230, v51, v51
	v_mul_f32_e32 v231, v53, v53
	global_store_dwordx2 v65, v[244:245], s[68:69] offset:256
	v_fmac_f32_e32 v230, v50, v50
	v_fmac_f32_e32 v231, v52, v52
	v_add_f32_e32 v230, v230, v231
	v_add_f32_e32 v63, v63, v230
	v_max3_f32 v64, |v50|, |v51|, v64
	v_max3_f32 v64, |v52|, |v53|, v64
	global_store_dwordx4 v62, v[46:49], s[98:99] offset:3072
	v_cvt_pk_bf16_f32 v246, v46, v47
	v_cvt_pk_bf16_f32 v247, v48, v49
	v_mul_f32_e32 v230, v47, v47
	v_mul_f32_e32 v231, v49, v49
	global_store_dwordx2 v65, v[246:247], s[68:69] offset:288
	v_fmac_f32_e32 v230, v46, v46
	v_fmac_f32_e32 v231, v48, v48
	v_add_f32_e32 v230, v230, v231
	v_add_f32_e32 v63, v63, v230
	v_max3_f32 v64, |v46|, |v47|, v64
	v_max3_f32 v64, |v48|, |v49|, v64
	ds_bpermute_b32 v238, v42, v63
	ds_bpermute_b32 v239, v42, v64
	s_waitcnt lgkmcnt(0)
	v_add_f32_e32 v63, v63, v238
	v_max_f32_e32 v64, v64, v239
	ds_bpermute_b32 v238, v43, v63
	ds_bpermute_b32 v239, v43, v64
	s_waitcnt lgkmcnt(0)
	v_add_f32_e32 v63, v63, v238
	v_max_f32_e32 v64, v64, v239
	s_mov_b64 exec, s[6:7]
	global_atomic_add_f32 v41, v63, s[10:11] offset:576
	global_atomic_umax v41, v64, s[12:13] offset:576
	s_mov_b64 exec, -1
	s_waitcnt vmcnt(34)
	v_pk_mul_f32 v[30:31], v[228:229], v[30:31] op_sel:[0,0] op_sel_hi:[0,1]
	v_pk_mul_f32 v[32:33], v[228:229], v[32:33] op_sel:[0,0] op_sel_hi:[0,1]
	v_pk_fma_f32 v[30:31], v[162:163], v[30:31], v[146:147]
	v_pk_fma_f32 v[32:33], v[164:165], v[32:33], v[148:149]
	v_pk_mul_f32 v[26:27], v[228:229], v[26:27] op_sel:[0,0] op_sel_hi:[0,1]
	v_pk_mul_f32 v[28:29], v[228:229], v[28:29] op_sel:[0,0] op_sel_hi:[0,1]
	v_pk_fma_f32 v[26:27], v[166:167], v[26:27], v[150:151]
	v_pk_fma_f32 v[28:29], v[168:169], v[28:29], v[152:153]
	v_pk_mul_f32 v[22:23], v[228:229], v[22:23] op_sel:[0,0] op_sel_hi:[0,1]
	v_pk_mul_f32 v[24:25], v[228:229], v[24:25] op_sel:[0,0] op_sel_hi:[0,1]
	v_pk_fma_f32 v[22:23], v[170:171], v[22:23], v[154:155]
	v_pk_fma_f32 v[24:25], v[172:173], v[24:25], v[156:157]
	v_pk_mul_f32 v[18:19], v[228:229], v[18:19] op_sel:[0,0] op_sel_hi:[0,1]
	v_pk_mul_f32 v[20:21], v[228:229], v[20:21] op_sel:[0,0] op_sel_hi:[0,1]
	v_pk_fma_f32 v[18:19], v[218:219], v[18:19], v[158:159]
	v_pk_fma_f32 v[20:21], v[220:221], v[20:21], v[160:161]
	v_add_u32_e32 v62, 0x6000, v36
	v_add_u32_e32 v65, 0x140000, v40
	global_store_dwordx4 v62, v[30:33], s[98:99] offset:0
	v_cvt_pk_bf16_f32 v240, v30, v31
	v_cvt_pk_bf16_f32 v241, v32, v33
	v_mul_f32_e32 v230, v31, v31
	v_mul_f32_e32 v231, v33, v33
	global_store_dwordx2 v65, v[240:241], s[68:69] offset:0
	v_fmac_f32_e32 v230, v30, v30
	v_fmac_f32_e32 v231, v32, v32
	v_add_f32_e32 v63, v230, v231
	v_max3_f32 v64, |v30|, |v31|, 0
	v_max3_f32 v64, |v32|, |v33|, v64
	global_store_dwordx4 v62, v[26:29], s[98:99] offset:1024
	v_cvt_pk_bf16_f32 v242, v26, v27
	v_cvt_pk_bf16_f32 v243, v28, v29
	v_mul_f32_e32 v230, v27, v27
	v_mul_f32_e32 v231, v29, v29
	global_store_dwordx2 v65, v[242:243], s[68:69] offset:32
	v_fmac_f32_e32 v230, v26, v26
	v_fmac_f32_e32 v231, v28, v28
	v_add_f32_e32 v230, v230, v231
	v_add_f32_e32 v63, v63, v230
	v_max3_f32 v64, |v26|, |v27|, v64
	v_max3_f32 v64, |v28|, |v29|, v64
	global_store_dwordx4 v62, v[22:25], s[98:99] offset:2048
	v_cvt_pk_bf16_f32 v244, v22, v23
	v_cvt_pk_bf16_f32 v245, v24, v25
	v_mul_f32_e32 v230, v23, v23
	v_mul_f32_e32 v231, v25, v25
	global_store_dwordx2 v65, v[244:245], s[68:69] offset:256
	v_fmac_f32_e32 v230, v22, v22
	v_fmac_f32_e32 v231, v24, v24
	v_add_f32_e32 v230, v230, v231
	v_add_f32_e32 v63, v63, v230
	v_max3_f32 v64, |v22|, |v23|, v64
	v_max3_f32 v64, |v24|, |v25|, v64
	global_store_dwordx4 v62, v[18:21], s[98:99] offset:3072
	v_cvt_pk_bf16_f32 v246, v18, v19
	v_cvt_pk_bf16_f32 v247, v20, v21
	v_mul_f32_e32 v230, v19, v19
	v_mul_f32_e32 v231, v21, v21
	global_store_dwordx2 v65, v[246:247], s[68:69] offset:288
	v_fmac_f32_e32 v230, v18, v18
	v_fmac_f32_e32 v231, v20, v20
	v_add_f32_e32 v230, v230, v231
	v_add_f32_e32 v63, v63, v230
	v_max3_f32 v64, |v18|, |v19|, v64
	v_max3_f32 v64, |v20|, |v21|, v64
	ds_bpermute_b32 v238, v42, v63
	ds_bpermute_b32 v239, v42, v64
	s_waitcnt lgkmcnt(0)
; template <class Epi, class Sched, bool ALIGN_EPI = false, bool SP2 = false, bool I8 = false>
; __device__ __forceinline__ void gemm_phase(PG8_LAS unsigned char* lds, const Gemm g, const Sched& S, const Epi& E) {
;     ...
;         if constexpr (!Epi::AFTER_DRAIN) { int t2 = threadIdx.x; asm volatile("" : "+v"(t2)); const int w2 = t2 >> 6, l2 = t2 & 63; E(acc, cur, w2 >> 2, w2 & 3, l2 & 15, l2 >> 4); S.done(cur); }
;         if (!has_next) break;
; #pragma unroll
;         for (int a = 0; a < 2; ++a)
; #pragma unroll
;             for (int b = 0; b < 2; ++b)
; #pragma unroll
;     __device__ __forceinline__ void operator()(const typename AccT<I8>::type (&acc)[2][2][4][2], const Unit& u, int wr, int wc, int fr, int fq) const {
;     ...
;         for (int s = 0; s < 8; ++s) { const int ai = s >> 2, m = s & 3; const int r = row0 + ai * HALF + m * 16; const size_t off = (size_t)r * 4096 + col0;
;                 if (s + 1 < 8) load_row(nxt, (size_t)(row0 + ((s + 1) >> 2) * HALF + ((s + 1) & 3) * 16) * 4096 + col0);
;                 const float rs = rsv[s];
;                 float ss = 0.f, mx = 0.f;
; #pragma unroll
;                 for (int bj = 0; bj < 2; ++bj)
; #pragma unroll
;                     for (int n = 0; n < 2; ++n) { const size_t o = off + bj * HALF + n * 16; const f32x4 b = cur.b[bj][n]; f32x4 v;
;                         if constexpr (I8) v = __builtin_convertvector(acc[ai][bj][m][n], f32x4) * rs * sv[bj][n]; else v = acc[ai][bj][m][n];
;                         if (MODE == 1) { const u32x2 pw = cur.pw[bj][n]; const f32x4 pp = (f32x4){bf_lo(pw.x), bf_hi(pw.x), bf_lo(pw.y), bf_hi(pw.y)}; v = sig4(I8 ? v : v * rs) * pp; }
;                         const f32x4 x = b + v; *(f32x4*)(out + o) = x;
;                         if (MODE == 0 && XB) { u32x2 w; w.x = cvt_pk_bf16(x[0], x[1]); w.y = cvt_pk_bf16(x[2], x[3]); *(u32x2*)(XB + o) = w; ss += (x[0] * x[0] + x[1] * x[1]) + (x[2] * x[2] + x[3] * x[3]);
;                             if (RM) mx = fmaxf(fmaxf(mx, fmaxf(fabsf(x[0]), fabsf(x[1]))), fmaxf(fabsf(x[2]), fabsf(x[3]))); } }
;                 if (MODE == 0 && XB) { ss += __shfl_xor(ss, 16); ss += __shfl_xor(ss, 32); if (fq == 0) unsafeAtomicAdd(SS + r, ss);
;                     if (RM) { mx = fmaxf(mx, __shfl_xor(mx, 16)); mx = fmaxf(mx, __shfl_xor(mx, 32)); if (fq == 0) atomicMax(RM + r, __builtin_bit_cast(unsigned, mx)); } }
;                 cur = nxt; }
	v_add_f32_e32 v63, v63, v238
	v_max_f32_e32 v64, v64, v239
	ds_bpermute_b32 v238, v43, v63
	ds_bpermute_b32 v239, v43, v64
	s_waitcnt lgkmcnt(0)
	v_add_f32_e32 v63, v63, v238
	v_max_f32_e32 v64, v64, v239
	s_mov_b64 exec, s[6:7]
	global_atomic_add_f32 v41, v63, s[10:11] offset:640
	global_atomic_umax v41, v64, s[12:13] offset:640
	s_mov_b64 exec, -1
	s_waitcnt vmcnt(30)
	v_pk_mul_f32 v[14:15], v[228:229], v[14:15] op_sel:[1,0] op_sel_hi:[1,1]
	v_pk_mul_f32 v[16:17], v[228:229], v[16:17] op_sel:[1,0] op_sel_hi:[1,1]
	v_pk_fma_f32 v[14:15], v[162:163], v[14:15], v[186:187]
	v_pk_fma_f32 v[16:17], v[164:165], v[16:17], v[188:189]
	v_pk_mul_f32 v[10:11], v[228:229], v[10:11] op_sel:[1,0] op_sel_hi:[1,1]
	v_pk_mul_f32 v[12:13], v[228:229], v[12:13] op_sel:[1,0] op_sel_hi:[1,1]
	v_pk_fma_f32 v[10:11], v[166:167], v[10:11], v[190:191]
	v_pk_fma_f32 v[12:13], v[168:169], v[12:13], v[192:193]
	v_pk_mul_f32 v[6:7], v[228:229], v[6:7] op_sel:[1,0] op_sel_hi:[1,1]
	v_pk_mul_f32 v[8:9], v[228:229], v[8:9] op_sel:[1,0] op_sel_hi:[1,1]
	v_pk_fma_f32 v[6:7], v[170:171], v[6:7], v[194:195]
	v_pk_fma_f32 v[8:9], v[172:173], v[8:9], v[196:197]
	v_pk_mul_f32 v[2:3], v[228:229], v[2:3] op_sel:[1,0] op_sel_hi:[1,1]
	v_pk_mul_f32 v[4:5], v[228:229], v[4:5] op_sel:[1,0] op_sel_hi:[1,1]
	v_pk_fma_f32 v[2:3], v[218:219], v[2:3], v[198:199]
	v_pk_fma_f32 v[4:5], v[220:221], v[4:5], v[200:201]
	v_add_u32_e32 v62, 0x7000, v36
	v_add_u32_e32 v65, 0x160000, v40
	global_store_dwordx4 v62, v[14:17], s[98:99] offset:0
	v_cvt_pk_bf16_f32 v240, v14, v15
	v_cvt_pk_bf16_f32 v241, v16, v17
	v_mul_f32_e32 v230, v15, v15
	v_mul_f32_e32 v231, v17, v17
	global_store_dwordx2 v65, v[240:241], s[68:69] offset:0
	v_fmac_f32_e32 v230, v14, v14
	v_fmac_f32_e32 v231, v16, v16
	v_add_f32_e32 v63, v230, v231
	v_max3_f32 v64, |v14|, |v15|, 0
	v_max3_f32 v64, |v16|, |v17|, v64
	global_store_dwordx4 v62, v[10:13], s[98:99] offset:1024
	v_cvt_pk_bf16_f32 v242, v10, v11
	v_cvt_pk_bf16_f32 v243, v12, v13
	v_mul_f32_e32 v230, v11, v11
	v_mul_f32_e32 v231, v13, v13
	global_store_dwordx2 v65, v[242:243], s[68:69] offset:32
	v_fmac_f32_e32 v230, v10, v10
	v_fmac_f32_e32 v231, v12, v12
	v_add_f32_e32 v230, v230, v231
	v_add_f32_e32 v63, v63, v230
	v_max3_f32 v64, |v10|, |v11|, v64
	v_max3_f32 v64, |v12|, |v13|, v64
	global_store_dwordx4 v62, v[6:9], s[98:99] offset:2048
	v_cvt_pk_bf16_f32 v244, v6, v7
	v_cvt_pk_bf16_f32 v245, v8, v9
	v_mul_f32_e32 v230, v7, v7
	v_mul_f32_e32 v231, v9, v9
	global_store_dwordx2 v65, v[244:245], s[68:69] offset:256
	v_fmac_f32_e32 v230, v6, v6
	v_fmac_f32_e32 v231, v8, v8
	v_add_f32_e32 v230, v230, v231
	v_add_f32_e32 v63, v63, v230
	v_max3_f32 v64, |v6|, |v7|, v64
	v_max3_f32 v64, |v8|, |v9|, v64
	global_store_dwordx4 v62, v[2:5], s[98:99] offset:3072
	v_cvt_pk_bf16_f32 v246, v2, v3
	v_cvt_pk_bf16_f32 v247, v4, v5
	v_mul_f32_e32 v230, v3, v3
	v_mul_f32_e32 v231, v5, v5
	global_store_dwordx2 v65, v[246:247], s[68:69] offset:288
	v_fmac_f32_e32 v230, v2, v2
	v_fmac_f32_e32 v231, v4, v4
	v_add_f32_e32 v230, v230, v231
	v_add_f32_e32 v63, v63, v230
	v_max3_f32 v64, |v2|, |v3|, v64
	v_max3_f32 v64, |v4|, |v5|, v64
	ds_bpermute_b32 v238, v42, v63
	ds_bpermute_b32 v239, v42, v64
	s_waitcnt lgkmcnt(0)
	v_add_f32_e32 v63, v63, v238
	v_max_f32_e32 v64, v64, v239
	ds_bpermute_b32 v238, v43, v63
	ds_bpermute_b32 v239, v43, v64
	s_waitcnt lgkmcnt(0)
	v_add_f32_e32 v63, v63, v238
	v_max_f32_e32 v64, v64, v239
	s_mov_b64 exec, s[6:7]
	global_atomic_add_f32 v41, v63, s[10:11] offset:704
	global_atomic_umax v41, v64, s[12:13] offset:704
	s_mov_b64 exec, -1
	v_readlane_b32 s68, v254, 8
	v_readlane_b32 s69, v254, 9
	v_readlane_b32 s70, v254, 10
	v_readlane_b32 s71, v254, 11
	v_readlane_b32 s72, v254, 12
	v_readlane_b32 s73, v254, 13
	v_readlane_b32 s74, v254, 14
	v_readlane_b32 s75, v254, 15
.LBB0_1780:
	s_andn2_b64 vcc, exec, s[4:5]
	s_mov_b64 s[2:3], -1
	s_cbranch_vccnz .LBB0_1713
	s_andn2_b64 vcc, exec, s[0:1]
	s_cbranch_vccnz .LBB0_1712
	s_barrier
	s_branch .LBB0_1712
.LBB0_1791:
	s_waitcnt vmcnt(0)
	s_barrier
